# barrier: wave 1 issues the CU's L1 invalidate right behind the arrival s_barrier and waits for it before the closing s_barrier, so thread 0's arrival/write-back/poll path never waits on it
# speedup vs baseline: 1.0133x; 1.0010x over previous
.LBB0_20:
	s_or_b64 exec, exec, s[0:1]
	s_mov_b64 s[0:1], 0
	s_waitcnt vmcnt(0) lgkmcnt(0)
	s_barrier

.LBB0_838:
	s_waitcnt vmcnt(0)
	s_waitcnt vmcnt(0) lgkmcnt(0)
	s_barrier
	v_readfirstlane_b32 s2, v224
	s_lshr_b32 s2, s2, 6
	s_cmp_lg_u32 s2, 1
	s_cbranch_scc1 .Lxb_noinv
	buffer_inv sc1
.Lxb_noinv:
	s_and_saveexec_b64 s[0:1], s[28:29]
	s_cbranch_execnz .LBB0_839
	s_getpc_b64 s[98:99]
